# DPP prefix-max in mLSTM chunk_out, padded so all later code keeps the previous version's byte offsets
# speedup vs baseline: 1.0092x; 1.0078x over previous
; template <bool IS_ML>
; __device__ __forceinline__ void chunk_out(LAS unsigned char* lds, unsigned char* ws, const float* w1, const float* w2, const float* onorm, int bid, int nb, int wid_s) {
;     ...
;       if (tid < 64) { const float mp = ((const float*)(ws + WS_SMALL + SM_MST))[c * 4 + h]; const float bt = GM(0)[tid]; const float inter = bt + mp;
;         float mx = -1e30f; for (int s = 0; s <= tid; ++s) mx = fmaxf(mx, GM(1)[s] - GM(0)[s]);
;         const float mt = fmaxf(inter, mx + bt); GM(2)[tid] = mt; GM(4)[tid] = __expf(inter - mt); GM(3)[tid] = 0.f; }
.LBB0_143:
	s_or_b64 exec, exec, s[36:37]
	s_waitcnt lgkmcnt(0)
	s_barrier
	s_and_saveexec_b64 s[54:55], s[0:1]
	s_cbranch_execz .LBB0_155
	s_ashr_i32 s89, s88, 31
	s_lshl_b64 s[30:31], s[88:89], 2
	v_readlane_b32 s36, v254, 48
	s_add_u32 s30, s36, s30
	v_readlane_b32 s36, v254, 45
	s_addc_u32 s31, s36, s31
	global_load_dword v5, v1, s[30:31]
	ds_read_b32 v4, v135
	ds_read_b32 v7, v135 offset:256
	s_mov_b64 s[68:69], exec
	s_waitcnt lgkmcnt(0)
	v_sub_f32_e32 v6, v7, v4
	s_nop 1
	v_max_f32_dpp v6, v6, v6 row_shr:1 row_mask:0xf bank_mask:0xf
	s_nop 1
	v_max_f32_dpp v6, v6, v6 row_shr:2 row_mask:0xf bank_mask:0xf
	s_nop 1
	v_max_f32_dpp v6, v6, v6 row_shr:4 row_mask:0xf bank_mask:0xf
	s_nop 1
	v_max_f32_dpp v6, v6, v6 row_shr:8 row_mask:0xf bank_mask:0xf
	s_nop 1
	v_max_f32_dpp v6, v6, v6 row_bcast:15 row_mask:0xa bank_mask:0xf
	s_nop 1
	v_max_f32_dpp v6, v6, v6 row_bcast:31 row_mask:0xc bank_mask:0xf
	s_nop 1
	v_max_f32_e32 v6, 0xf149f2ca, v6
	s_branch .LBB0_154
	s_nop 0
	s_nop 0
	s_nop 0
	s_nop 0
	s_nop 0
	s_nop 0
	s_nop 0
	s_nop 0
	s_nop 0
	s_nop 0
	s_nop 0
	s_nop 0
	s_nop 0
	s_nop 0
	s_nop 0
	s_nop 0
	s_nop 0
	s_nop 0
	s_nop 0
	s_nop 0
	s_nop 0
	s_nop 0
	s_nop 0
	s_nop 0
	s_nop 0
	s_nop 0
	s_nop 0
	s_nop 0
	s_nop 0
	s_nop 0
	s_nop 0
	s_nop 0
	s_nop 0
	s_nop 0
	s_nop 0
	s_nop 0
	s_nop 0
	s_nop 0
	s_nop 0
	s_nop 0
	s_nop 0
	s_nop 0
	s_nop 0
	s_nop 0
	s_nop 0
	s_nop 0
	s_nop 0
	s_nop 0
	s_nop 0
	s_nop 0
	s_nop 0
	s_nop 0
	s_nop 0
	s_nop 0
	s_nop 0
	s_nop 0
	s_nop 0
	s_nop 0
	s_nop 0
	s_nop 0
	s_nop 0
	s_nop 0
	s_nop 0
	s_nop 0
	s_nop 0
	s_nop 0
	s_nop 0
	s_nop 0
	s_nop 0
	s_nop 0
	s_nop 0
	s_nop 0
	s_nop 0
	s_nop 0
	s_nop 0
	s_nop 0
	s_nop 0
	s_nop 0
	s_nop 0
	s_nop 0
	s_nop 0
	s_nop 0
	s_nop 0
	s_nop 0
	s_nop 0
